# packed softmax subtract/sum with exps interleaved (no long transcendental bursts)
# speedup vs baseline: 1.0076x; 1.0051x over previous
.LBB0_582:
	v_pk_add_f32 v[134:135], v[134:135], v[224:225] op_sel_hi:[1,0] neg_lo:[0,1] neg_hi:[0,1]
	v_pk_add_f32 v[136:137], v[136:137], v[224:225] op_sel_hi:[1,0] neg_lo:[0,1] neg_hi:[0,1]
	v_exp_f32_e32 v134, v134
	v_exp_f32_e32 v135, v135
	v_pk_add_f32 v[138:139], v[138:139], v[224:225] op_sel_hi:[1,0] neg_lo:[0,1] neg_hi:[0,1]
	v_exp_f32_e32 v136, v136
	v_exp_f32_e32 v137, v137
	v_pk_add_f32 v[140:141], v[140:141], v[224:225] op_sel_hi:[1,0] neg_lo:[0,1] neg_hi:[0,1]
	v_exp_f32_e32 v138, v138
	v_exp_f32_e32 v139, v139
	v_pk_add_f32 v[234:235], v[146:147], v[224:225] op_sel_hi:[1,0] neg_lo:[0,1] neg_hi:[0,1]
	v_pk_add_f32 v[246:247], v[134:135], v[136:137]
	v_exp_f32_e32 v140, v140
	v_exp_f32_e32 v141, v141
	v_pk_add_f32 v[236:237], v[148:149], v[224:225] op_sel_hi:[1,0] neg_lo:[0,1] neg_hi:[0,1]
	v_pk_add_f32 v[246:247], v[246:247], v[138:139]
	v_exp_f32_e32 v234, v234
	v_exp_f32_e32 v235, v235
	v_pk_add_f32 v[238:239], v[142:143], v[224:225] op_sel_hi:[1,0] neg_lo:[0,1] neg_hi:[0,1]
	v_pk_add_f32 v[246:247], v[246:247], v[140:141]
	v_exp_f32_e32 v236, v236
	v_exp_f32_e32 v237, v237
	v_pk_add_f32 v[244:245], v[144:145], v[224:225] op_sel_hi:[1,0] neg_lo:[0,1] neg_hi:[0,1]
	v_pk_add_f32 v[246:247], v[246:247], v[234:235]
	v_exp_f32_e32 v238, v238
	v_exp_f32_e32 v239, v239
	v_pk_add_f32 v[226:227], v[150:151], v[222:223] op_sel:[0,1] op_sel_hi:[1,1] neg_lo:[0,1] neg_hi:[0,1]
	v_pk_add_f32 v[246:247], v[246:247], v[236:237]
	v_exp_f32_e32 v244, v244
	v_exp_f32_e32 v245, v245
	v_pk_add_f32 v[228:229], v[152:153], v[222:223] op_sel:[0,1] op_sel_hi:[1,1] neg_lo:[0,1] neg_hi:[0,1]
	v_pk_add_f32 v[246:247], v[246:247], v[238:239]
	v_exp_f32_e32 v226, v226
	v_exp_f32_e32 v227, v227
	v_pk_add_f32 v[230:231], v[154:155], v[222:223] op_sel:[0,1] op_sel_hi:[1,1] neg_lo:[0,1] neg_hi:[0,1]
	v_pk_add_f32 v[246:247], v[246:247], v[244:245]
	v_exp_f32_e32 v228, v228
	v_exp_f32_e32 v229, v229
	v_pk_add_f32 v[232:233], v[156:157], v[222:223] op_sel:[0,1] op_sel_hi:[1,1] neg_lo:[0,1] neg_hi:[0,1]
	v_exp_f32_e32 v230, v230
	v_exp_f32_e32 v231, v231
	v_pk_add_f32 v[158:159], v[158:159], v[222:223] op_sel:[0,1] op_sel_hi:[1,1] neg_lo:[0,1] neg_hi:[0,1]
	v_pk_add_f32 v[248:249], v[226:227], v[228:229]
	v_exp_f32_e32 v232, v232
	v_exp_f32_e32 v233, v233
	v_pk_add_f32 v[160:161], v[160:161], v[222:223] op_sel:[0,1] op_sel_hi:[1,1] neg_lo:[0,1] neg_hi:[0,1]
	v_pk_add_f32 v[248:249], v[248:249], v[230:231]
	v_exp_f32_e32 v158, v158
	v_exp_f32_e32 v159, v159
	v_pk_add_f32 v[162:163], v[162:163], v[222:223] op_sel:[0,1] op_sel_hi:[1,1] neg_lo:[0,1] neg_hi:[0,1]
	v_pk_add_f32 v[248:249], v[248:249], v[232:233]
	v_exp_f32_e32 v160, v160
	v_exp_f32_e32 v161, v161
	v_pk_add_f32 v[164:165], v[164:165], v[222:223] op_sel:[0,1] op_sel_hi:[1,1] neg_lo:[0,1] neg_hi:[0,1]
	v_pk_add_f32 v[248:249], v[248:249], v[158:159]
	v_exp_f32_e32 v162, v162
	v_exp_f32_e32 v163, v163
	v_pk_add_f32 v[248:249], v[248:249], v[160:161]
	v_exp_f32_e32 v164, v164
	v_exp_f32_e32 v165, v165
	v_pk_add_f32 v[248:249], v[248:249], v[162:163]
	s_nop 0
	v_pk_add_f32 v[248:249], v[248:249], v[164:165]
	v_add_f32_e32 v241, v246, v247
	v_fmac_f32_e32 v241, v191, v208
	v_add_f32_e32 v191, v248, v249
	s_mul_i32 s0, s24, 0x4800
	v_fmac_f32_e32 v191, v203, v206
	v_add_u32_e32 v203, s0, v197
	v_cvt_pk_bf16_f32 v154, v158, v159
	v_add_u32_e32 v206, 0xc800, v203
	v_add_u32_e32 v158, 0xd000, v203
	v_cvt_pk_bf16_f32 v155, v160, v161
	v_cvt_pk_bf16_f32 v134, v134, v135
	v_cvt_pk_bf16_f32 v135, v136, v137
	v_cvt_pk_bf16_f32 v136, v138, v139
	v_cvt_pk_bf16_f32 v137, v140, v141
	ds_read2_b64 v[138:141], v206 offset1:4
	ds_read2_b64 v[142:145], v206 offset0:8 offset1:12
	ds_read2_b64 v[146:149], v158 offset0:32 offset1:36
	ds_read2_b64 v[158:161], v158 offset0:40 offset1:44
	v_cvt_pk_bf16_f32 v150, v226, v227
	v_cvt_pk_bf16_f32 v151, v228, v229
	v_cvt_pk_bf16_f32 v152, v230, v231
	v_cvt_pk_bf16_f32 v153, v232, v233
	v_cvt_pk_bf16_f32 v156, v162, v163
	v_cvt_pk_bf16_f32 v157, v164, v165
	v_cvt_pk_bf16_f32 v162, v234, v235
	v_cvt_pk_bf16_f32 v163, v236, v237
	v_cvt_pk_bf16_f32 v164, v238, v239
	v_cvt_pk_bf16_f32 v165, v244, v245
	s_waitcnt lgkmcnt(3)
	v_mfma_f32_16x16x32_bf16 v[62:65], v[138:141], v[150:153], v[62:65]
	v_mfma_f32_16x16x32_bf16 v[30:33], v[138:141], v[134:137], v[30:33]
	s_waitcnt lgkmcnt(2)
	v_mfma_f32_16x16x32_bf16 v[62:65], v[142:145], v[154:157], v[62:65]
	v_mfma_f32_16x16x32_bf16 v[30:33], v[142:145], v[162:165], v[30:33]
	v_add_u32_e32 v142, 0xd800, v203
	ds_read2_b64 v[138:141], v142 offset0:64 offset1:68
	ds_read2_b64 v[142:145], v142 offset0:72 offset1:76
	s_waitcnt lgkmcnt(3)
	v_mfma_f32_16x16x32_bf16 v[58:61], v[146:149], v[150:153], v[58:61]
	v_mfma_f32_16x16x32_bf16 v[26:29], v[146:149], v[134:137], v[26:29]
	s_waitcnt lgkmcnt(2)
	v_mfma_f32_16x16x32_bf16 v[58:61], v[158:161], v[154:157], v[58:61]
	v_mfma_f32_16x16x32_bf16 v[26:29], v[158:161], v[162:165], v[26:29]
	v_add_u32_e32 v158, 0xe000, v203
	ds_read2_b64 v[146:149], v158 offset0:96 offset1:100
	ds_read2_b64 v[158:161], v158 offset0:104 offset1:108
	s_waitcnt lgkmcnt(3)
	v_mfma_f32_16x16x32_bf16 v[54:57], v[138:141], v[150:153], v[54:57]
	v_mfma_f32_16x16x32_bf16 v[22:25], v[138:141], v[134:137], v[22:25]
	s_waitcnt lgkmcnt(2)
	v_mfma_f32_16x16x32_bf16 v[54:57], v[142:145], v[154:157], v[54:57]
	v_mfma_f32_16x16x32_bf16 v[22:25], v[142:145], v[162:165], v[22:25]
	v_add_u32_e32 v142, 0xe800, v203
	ds_read2_b64 v[138:141], v142 offset0:128 offset1:132
	ds_read2_b64 v[142:145], v142 offset0:136 offset1:140
	s_waitcnt lgkmcnt(3)
	v_mfma_f32_16x16x32_bf16 v[50:53], v[146:149], v[150:153], v[50:53]
	v_mfma_f32_16x16x32_bf16 v[18:21], v[146:149], v[134:137], v[18:21]
	s_waitcnt lgkmcnt(2)
	v_mfma_f32_16x16x32_bf16 v[50:53], v[158:161], v[154:157], v[50:53]
	v_mfma_f32_16x16x32_bf16 v[18:21], v[158:161], v[162:165], v[18:21]
	v_add_u32_e32 v158, 0xf000, v203
	ds_read2_b64 v[146:149], v158 offset0:160 offset1:164
	ds_read2_b64 v[158:161], v158 offset0:168 offset1:172
	s_waitcnt lgkmcnt(3)
	v_mfma_f32_16x16x32_bf16 v[46:49], v[138:141], v[150:153], v[46:49]
	v_mfma_f32_16x16x32_bf16 v[14:17], v[138:141], v[134:137], v[14:17]
	s_waitcnt lgkmcnt(2)
	v_mfma_f32_16x16x32_bf16 v[46:49], v[142:145], v[154:157], v[46:49]
	v_mfma_f32_16x16x32_bf16 v[14:17], v[142:145], v[162:165], v[14:17]
	v_add_u32_e32 v142, 0xf800, v203
	ds_read2_b64 v[138:141], v142 offset0:192 offset1:196
	ds_read2_b64 v[142:145], v142 offset0:200 offset1:204
	s_waitcnt lgkmcnt(3)
	v_mfma_f32_16x16x32_bf16 v[42:45], v[146:149], v[150:153], v[42:45]
	v_mfma_f32_16x16x32_bf16 v[10:13], v[146:149], v[134:137], v[10:13]
	s_waitcnt lgkmcnt(2)
	v_mfma_f32_16x16x32_bf16 v[42:45], v[158:161], v[154:157], v[42:45]
	v_mfma_f32_16x16x32_bf16 v[10:13], v[158:161], v[162:165], v[10:13]
	v_add_u32_e32 v158, 0x3800, v206
	ds_read2_b64 v[146:149], v158 offset0:224 offset1:228
	ds_read2_b64 v[158:161], v158 offset0:232 offset1:236
	s_waitcnt lgkmcnt(3)
	v_mfma_f32_16x16x32_bf16 v[38:41], v[138:141], v[150:153], v[38:41]
	v_mfma_f32_16x16x32_bf16 v[6:9], v[138:141], v[134:137], v[6:9]
	s_waitcnt lgkmcnt(2)
	v_mfma_f32_16x16x32_bf16 v[38:41], v[142:145], v[154:157], v[38:41]
	v_mfma_f32_16x16x32_bf16 v[6:9], v[142:145], v[162:165], v[6:9]
	s_waitcnt lgkmcnt(1)
	v_mfma_f32_16x16x32_bf16 v[34:37], v[146:149], v[150:153], v[34:37]
	v_mfma_f32_16x16x32_bf16 v[2:5], v[146:149], v[134:137], v[2:5]
	s_waitcnt lgkmcnt(0)
	v_mfma_f32_16x16x32_bf16 v[34:37], v[158:161], v[154:157], v[34:37]
	v_mfma_f32_16x16x32_bf16 v[2:5], v[158:161], v[162:165], v[2:5]
	v_mov_b32_e32 v203, v191
	v_mov_b32_e32 v191, v241
	s_andn2_b64 vcc, exec, s[6:7]
	s_mov_b64 s[0:1], -1
	s_cbranch_vccz .LBB0_584
	s_branch .LBB0_585
